# static s_setprio 1 for waves 4-7 during the scan + neighbourhood-attention phase
# baseline (speedup 1.0000x reference)
; __global__ void __launch_bounds__(NTHREADS, 2) fwd_kernel(Params p) {
;     ...
;     if (RUN(3)) {
;         const int vcu = (G % 8 == 0) ? (cid & 7) * (G >> 3) + (cid >> 3) : cid;
;         if (p.flags & 1) for (int v = vcu; v < 256; v += G) { const int bh = v >> 3, g_ = (v >> 2) & 1, es_ = v & 3; scan_item(p, (g_ * 32 + bh) * 4 + es_, lds); }
.LBB0_290:
	v_readlane_b32 s4, v246, 12
	s_cmp_lt_i32 s4, 4
	s_cselect_b64 s[66:67], -1, 0
	s_and_b64 s[0:1], s[66:67], s[0:1]
	s_andn2_b64 vcc, exec, s[0:1]
	v_readlane_b32 s5, v246, 13
	v_readlane_b32 s6, v246, 14
	v_readlane_b32 s7, v246, 15
	s_cbranch_vccnz .LBB0_466
	v_readfirstlane_b32 s98, v144
	s_nop 3
	s_lshr_b32 s98, s98, 6
	s_cmp_ge_u32 s98, 4
	s_cbranch_scc0 .Lprio3_skip
	s_setprio 1
.Lprio3_skip:
	s_and_b32 s0, s34, 7
	s_cmp_lg_u32 s0, 0
	v_readlane_b32 s0, v246, 0
	s_mov_b32 s38, s0
	v_readlane_b32 s1, v246, 1
	s_cbranch_scc1 .LBB0_293
	v_readlane_b32 s0, v246, 0
	v_readlane_b32 s1, v246, 1
	s_mov_b32 s2, s0
	s_and_b32 s0, s0, 7
	s_ashr_i32 s1, s34, 3
	s_mul_i32 s0, s1, s0
	s_ashr_i32 s1, s2, 3
	s_add_i32 s38, s0, s1

; __device__ __forceinline__ void xcd_barrier(const XcdBarrier& b) {
;     asm volatile("s_waitcnt vmcnt(0)" ::: "memory");
;     __syncthreads();
;     if (threadIdx.x == 0) {
;         unsigned* bar = b.bar;
;         __builtin_amdgcn_s_waitcnt(0);
;         unsigned nloc = b.st[0], nx = b.st[1];
;         if (nloc == 0u) { xcd_barrier_complete(bar, b.x, nloc, nx); b.st[0] = nloc; b.st[1] = nx; }
.LBB0_466:
	s_setprio 0
	v_readlane_b32 s0, v246, 12
	v_readlane_b32 s1, v246, 13
	s_cmp_gt_i32 s1, 4
	v_readlane_b32 s2, v246, 14
	v_readlane_b32 s3, v246, 15
	s_cselect_b64 s[0:1], -1, 0
	s_and_b64 s[2:3], s[66:67], s[0:1]
	s_andn2_b64 vcc, exec, s[2:3]
	s_cbranch_vccnz .LBB0_520
	s_waitcnt vmcnt(0)
	s_waitcnt vmcnt(0) lgkmcnt(0)
	s_barrier
	s_mov_b64 s[2:3], exec
	v_readlane_b32 s4, v246, 23
	v_readlane_b32 s5, v246, 24
	s_and_b64 s[4:5], s[2:3], s[4:5]
	s_mov_b64 exec, s[4:5]
	s_cbranch_execz .LBB0_519
	s_add_i32 s4, 0, 0x23fe0
	v_mov_b32_e32 v0, s4
	s_waitcnt vmcnt(0) expcnt(0) lgkmcnt(0)
	ds_read_b32 v2, v0
	s_add_i32 s4, 0, 0x23fe4
	v_mov_b32_e32 v0, s4
	ds_read_b32 v0, v0
	s_waitcnt lgkmcnt(1)
	v_cmp_ne_u32_e32 vcc, 0, v2
	s_cbranch_vccnz .LBB0_483
	v_readlane_b32 s4, v246, 16
	v_readlane_b32 s5, v246, 17
	s_load_dwordx2 s[8:9], s[4:5], 0x4
	v_readlane_b32 s10, v246, 18
	v_readlane_b32 s11, v246, 19
	s_add_u32 s4, s10, 0x1000
	s_addc_u32 s5, s11, 0
	s_add_u32 s6, s10, 0x1100
	s_addc_u32 s7, s11, 0
	s_waitcnt lgkmcnt(0)
	s_mul_i32 s20, s8, s34
	s_add_u32 s8, s10, 0x1200
	s_mul_i32 s20, s20, s9
	s_addc_u32 s9, s11, 0
	s_add_u32 s10, s10, 0x1300
	s_addc_u32 s11, s11, 0
	s_mov_b32 s21, 1
	v_mov_b32_e32 v16, 0
	s_branch .LBB0_471

; __global__ void __launch_bounds__(NTHREADS, 2) fwd_kernel(Params p) {
	.amdhsa_kernel _Z10fwd_kernel6Params
		.amdhsa_group_segment_fixed_size 0
		.amdhsa_private_segment_fixed_size 0
		.amdhsa_kernarg_size 440
		.amdhsa_user_sgpr_count 2
		.amdhsa_user_sgpr_dispatch_ptr 0
		.amdhsa_user_sgpr_queue_ptr 0
		.amdhsa_user_sgpr_kernarg_segment_ptr 1
		.amdhsa_user_sgpr_dispatch_id 0
		.amdhsa_user_sgpr_kernarg_preload_length 0
		.amdhsa_user_sgpr_kernarg_preload_offset 0
		.amdhsa_user_sgpr_private_segment_size 0
		.amdhsa_uses_dynamic_stack 0
		.amdhsa_enable_private_segment 0
		.amdhsa_system_sgpr_workgroup_id_x 1
		.amdhsa_system_sgpr_workgroup_id_y 0
		.amdhsa_system_sgpr_workgroup_id_z 0
		.amdhsa_system_sgpr_workgroup_info 0
		.amdhsa_system_vgpr_workitem_id 2
		.amdhsa_next_free_vgpr 247
		.amdhsa_next_free_sgpr 99
		.amdhsa_accum_offset 248
		.amdhsa_reserve_vcc 1
		.amdhsa_float_round_mode_32 0
		.amdhsa_float_round_mode_16_64 0
		.amdhsa_float_denorm_mode_32 3
		.amdhsa_float_denorm_mode_16_64 3
		.amdhsa_dx10_clamp 1
		.amdhsa_ieee_mode 1
		.amdhsa_fp16_overflow 0
		.amdhsa_tg_split 0
		.amdhsa_exception_fp_ieee_invalid_op 0
		.amdhsa_exception_fp_denorm_src 0
		.amdhsa_exception_fp_ieee_div_zero 0
		.amdhsa_exception_fp_ieee_overflow 0
		.amdhsa_exception_fp_ieee_underflow 0
		.amdhsa_exception_fp_ieee_inexact 0
		.amdhsa_exception_int_div_zero 0
	.end_amdhsa_kernel

; __global__ void __launch_bounds__(NTHREADS, 2) fwd_kernel(Params p) {
amdhsa.kernels:
  - .agpr_count:     0
    .args:
      - .offset:         0
        .size:           184
        .value_kind:     by_value
      - .offset:         184
        .size:           4
        .value_kind:     hidden_block_count_x
      - .offset:         188
        .size:           4
        .value_kind:     hidden_block_count_y
      - .offset:         192
        .size:           4
        .value_kind:     hidden_block_count_z
      - .offset:         196
        .size:           2
        .value_kind:     hidden_group_size_x
      - .offset:         198
        .size:           2
        .value_kind:     hidden_group_size_y
      - .offset:         200
        .size:           2
        .value_kind:     hidden_group_size_z
      - .offset:         202
        .size:           2
        .value_kind:     hidden_remainder_x
      - .offset:         204
        .size:           2
        .value_kind:     hidden_remainder_y
      - .offset:         206
        .size:           2
        .value_kind:     hidden_remainder_z
      - .offset:         224
        .size:           8
        .value_kind:     hidden_global_offset_x
      - .offset:         232
        .size:           8
        .value_kind:     hidden_global_offset_y
      - .offset:         240
        .size:           8
        .value_kind:     hidden_global_offset_z
      - .offset:         248
        .size:           2
        .value_kind:     hidden_grid_dims
      - .offset:         272
        .size:           8
        .value_kind:     hidden_multigrid_sync_arg
      - .offset:         304
        .size:           4
        .value_kind:     hidden_dynamic_lds_size
    .group_segment_fixed_size: 0
    .kernarg_segment_align: 8
    .kernarg_segment_size: 440
    .language:       OpenCL C
    .language_version:
      - 2
      - 0
    .max_flat_workgroup_size: 512
    .name:           _Z10fwd_kernel6Params
    .private_segment_fixed_size: 0
    .sgpr_count:     105
    .sgpr_spill_count: 189
    .symbol:         _Z10fwd_kernel6Params.kd
    .uniform_work_group_size: 1
    .uses_dynamic_stack: false
    .vgpr_count:     247
    .vgpr_spill_count: 0
    .wavefront_size: 64
